# same-layer windows, in-proj-tail window 3 iterations (A=3,P=3,B=2)
# speedup vs baseline: 1.0045x; 1.0032x over previous
; #define LAS __attribute__((address_space(3)))
; __device__ __forceinline__ void convert_layer_static(const PT& a, LAS unsigned char* lds, int l, int gw, int NGW, int wave, int lane, int r_end = IT_LAYER) {
;     for (int r = 2 * gw; r < r_end; r += 2 * NGW) cv_pair(a, lds, l, r, wave, lane);
; }
; __device__ __forceinline__ void prologue_a(const PT& a, LAS unsigned char* lds) {
;     ...
;     convert_layer_static(a, lds, 0, gw, NGW, wave, lane);
;     for (int cl_ = 1; cl_ < DEPTH; ++cl_) convert_layer_static(a, lds, cl_, gw, NGW, wave, lane, CV_PRO_ITEMS);
.LBB0_22:
	s_or_saveexec_b64 s[12:13], s[0:1]
	v_lshlrev_b32_e32 v109, 1, v66
	v_readlane_b32 s0, v252, 4
	v_mul_lo_u32 v3, v12, s6
	s_lshl_b32 s17, s0, 4
	v_add_u32_e32 v115, 0, v3
	v_lshlrev_b32_e32 v111, 5, v109
	v_readlane_b32 s1, v252, 5
	s_xor_b64 exec, exec, s[12:13]
	s_cbranch_execz .LBB0_110
	v_and_b32_e32 v74, 28, v68
	v_and_b32_e32 v76, 56, v2
	v_mov_b32_e32 v79, 0
	v_lshl_add_u32 v3, v74, 2, v115
	v_mul_u32_u24_e32 v121, 0x84, v67
	v_mul_u32_u24_e32 v113, 0x84, v76
	v_lshlrev_b32_e32 v2, 2, v67
	v_mov_b32_e32 v75, v79
	v_or_b32_e32 v69, 8, v67
	v_or_b32_e32 v97, 16, v67
	v_or_b32_e32 v99, 24, v67
	v_or_b32_e32 v101, 32, v67
	v_or_b32_e32 v103, 40, v67
	v_or_b32_e32 v105, 48, v67
	v_or_b32_e32 v107, 56, v67
	v_mov_b32_e32 v77, v79
	v_add3_u32 v117, v115, v113, v2
	v_lshlrev_b32_e32 v119, 5, v109
	s_lshl_b32 s36, s17, 5
	s_mov_b64 s[18:19], 0
	s_movk_i32 s37, 0x393f
	s_movk_i32 s38, 0x453f
	s_movk_i32 s39, 0x4d3f
	s_movk_i32 s40, 0x793f
	s_movk_i32 s41, 0x15ff
	s_movk_i32 s42, 0xba3
	s_movk_i32 s43, 0x1600
	s_movk_i32 s44, 0x3ff
	s_mov_b64 s[20:21], 0xea00000
	s_mov_b32 s45, 0x478bbced
	s_movk_i32 s46, 0x9f
	s_movk_i32 s47, 0x109
	v_lshlrev_b32_e32 v78, 2, v74
	v_add_u32_e32 v123, v3, v121
	v_lshlrev_b32_e32 v80, 1, v76
	s_mov_b32 s48, 0x533f
	v_readlane_b32 s100, v252, 4
	s_cmp_eq_u32 s100, 0x100
	s_cselect_b32 s48, s48, 0x8f3f
	v_mov_b32_e32 v127, 0xea00
	v_mov_b32_e32 v129, 5
	v_mov_b32_e32 v130, 0x23a40
	v_mov_b32_e32 v131, 0x23a38
	v_mov_b32_e32 v132, 6
	v_mov_b32_e32 v133, 0x80
	v_mov_b32_e32 v134, 0x23a20
	v_mov_b32_e32 v135, 0x23a18
	v_mov_b32_e32 v136, 0x23a10
	v_mov_b32_e32 v137, v109
	s_branch .LBB0_25

; #define LAS __attribute__((address_space(3)))
; __device__ __forceinline__ void convert_layer_static(const PT& a, LAS unsigned char* lds, int l, int gw, int NGW, int wave, int lane, int r_end = IT_LAYER) {
;     for (int r = 2 * gw; r < r_end; r += 2 * NGW) cv_pair(a, lds, l, r, wave, lane);
; }
; __device__ __forceinline__ void prologue_a(const PT& a, LAS unsigned char* lds) {
;     ...
;     convert_layer_static(a, lds, 0, gw, NGW, wave, lane);
;     for (int cl_ = 1; cl_ < DEPTH; ++cl_) convert_layer_static(a, lds, cl_, gw, NGW, wave, lane, CV_PRO_ITEMS);
.LBB0_110:
	s_or_b64 exec, exec, s[12:13]
	v_lshl_add_u32 v2, v74, 2, v115
	v_add_u32_e32 v3, v115, v113
	s_mov_b32 s13, 0
	v_lshl_add_u32 v113, v67, 2, v3
	v_lshl_add_u32 v115, v69, 2, v3
	v_lshl_add_u32 v117, v97, 2, v3
	v_lshl_add_u32 v119, v99, 2, v3
	s_mov_b32 s18, 1
	s_lshl_b32 s42, s17, 5
	s_movk_i32 s43, 0x393f
	s_movk_i32 s44, 0x453f
	s_movk_i32 s45, 0x4d3f
	s_movk_i32 s46, 0x793f
	s_movk_i32 s47, 0x15ff
	s_movk_i32 s48, 0xba3
	s_movk_i32 s49, 0x1600
	s_movk_i32 s50, 0x3ff
	v_mov_b32_e32 v79, 0
	s_mov_b64 s[20:21], 0xea00000
	s_mov_b32 s51, 0x478bbced
	s_movk_i32 s52, 0x9f
	s_movk_i32 s53, 0x109
	v_add_u32_e32 v121, v2, v121
	v_lshlrev_b64 v[76:77], 1, v[76:77]
	s_mov_b32 s54, 0x433f
	v_readlane_b32 s100, v252, 4
	s_cmp_eq_u32 s100, 0x100
	s_cselect_b32 s54, s54, 0x8f3f
	v_mov_b32_e32 v123, 0xea00
	v_mov_b32_e32 v125, 5
	v_mov_b32_e32 v128, 0x23a40
	v_mov_b32_e32 v129, 0x23a38
	v_mov_b32_e32 v130, 6
	v_mov_b32_e32 v131, 0x80
	v_mov_b32_e32 v132, 0x23a20
	v_mov_b32_e32 v133, 0x23a18
	v_mov_b32_e32 v134, 0x23a10
	s_branch .LBB0_112

; __device__ __forceinline__ int opaque_tid() { int t = threadIdx.x; asm volatile("" : "+v"(t)); return t; }
;     for (int it = 0; it < budget; ++it) {
;         unsigned r = 0; if (lane == 0) r = __hip_atomic_fetch_add(ctr, 2u, __ATOMIC_RELAXED, __HIP_MEMORY_SCOPE_AGENT);
;         r = (unsigned)__builtin_amdgcn_readfirstlane((int)r) + (unsigned)CV_PRO_ITEMS;
;         if (r >= (unsigned)IT_LAYER) break;
;         cv_pair(a, lds, l, (int)r, wave, lane);
;     }
; }
; __global__ void __launch_bounds__(NTHREADS, 2) mk_fwd(Args args) {
;     ...
;             if (l + 1 < DEPTH && !(G >= 256 && bid < 128)) { __syncthreads(); const int tid_ = opaque_tid(); convert_layer_queue(pt, lds, l + 1, cvq, tid_ >> 6, tid_ & 63); }
.LBB0_560:
	v_readlane_b32 s0, v252, 4
	s_cmp_lg_u32 s0, 0x100
	s_cbranch_scc1 .LcvqA_ret
	v_readlane_b32 s0, v252, 0
	v_readlane_b32 s36, v255, 0
	s_cmp_lt_u32 s0, 64
	s_cbranch_scc1 .LcvqA_ret
	s_mov_b32 s64, s36
	v_readlane_b32 s0, v254, 53
	v_readlane_b32 s1, v254, 54
	s_mov_b32 s3, s1
	s_lshl_b32 s2, s36, 6
	s_lshl_b64 s[0:1], s[2:3], 2
	v_readlane_b32 s4, v254, 60
	v_readlane_b32 s5, v254, 61
	s_add_u32 s0, s4, s0
	s_addc_u32 s1, s5, s1
	s_add_u32 s0, s0, 0x8000
	s_addc_u32 s1, s1, 0
	s_add_i32 s2, s36, 0
	s_mul_hi_u32 s33, s2, 0x2c00000
	s_mul_i32 s34, s2, 0x2c00000
	s_mul_hi_u32 s35, s2, 0x1600000
	s_mul_i32 s50, s2, 0x1600000
	s_lshl_b32 s6, s2, 11
	s_mov_b32 s7, s3
	s_lshl_b64 s[8:9], s[2:3], 24
	s_lshl_b64 s[10:11], s[2:3], 23
	s_mul_hi_u32 s51, s2, 0xc00000
	s_mul_i32 s52, s2, 0xc00000
	s_mul_hi_u32 s53, s2, 0x7280000
	s_mul_i32 s54, s2, 0x7280000
	s_mul_hi_u32 s55, s2, 0x3a00000
	v_writelane_b32 v254, s2, 53
	v_mov_b32_e32 v2, v0
	s_mul_i32 s56, s2, 0x3a00000
	v_writelane_b32 v254, s3, 54
	s_waitcnt vmcnt(0) lgkmcnt(0)
	s_barrier
	s_movk_i32 s2, 0x4200
	v_lshrrev_b32_e32 v1, 6, v2
	v_and_b32_e32 v3, 63, v2
	v_readfirstlane_b32 s100, v1
	v_readlane_b32 s101, v252, 0
	s_sub_u32 s101, s101, 64
	s_lshl_b32 s101, s101, 3
	s_add_u32 s100, s100, s101
	s_lshl_b32 s100, s100, 1
	s_add_u32 s100, s100, 0x1000
	v_mul_lo_u32 v1, v1, s2
	v_cmp_eq_u32_e64 s[40:41], 0, v3
	v_add_u32_e32 v3, 0, v1
	v_lshlrev_b32_e32 v1, 2, v2
	v_and_b32_e32 v66, 28, v1
	v_bfe_u32 v1, v2, 3, 3
	v_lshlrev_b32_e32 v2, 3, v2
	v_and_b32_e32 v68, 56, v2
	v_lshl_add_u32 v4, v66, 2, v3
	v_mul_u32_u24_e32 v5, 0x84, v1
	v_mul_u32_u24_e32 v2, 0x84, v68
	v_lshlrev_b32_e32 v6, 2, v1
	v_or_b32_e32 v67, 8, v1
	v_or_b32_e32 v69, 16, v1
	v_or_b32_e32 v71, 24, v1
	v_or_b32_e32 v73, 32, v1
	v_or_b32_e32 v75, 40, v1
	v_or_b32_e32 v77, 48, v1
	v_or_b32_e32 v79, 56, v1
	v_add3_u32 v81, v3, v2, v6
	s_mov_b32 s57, 0x3
	v_add_u32_e32 v83, v4, v5
	s_branch .LcvqA_1381

;     __device__ __forceinline__ const float* in(int i) const { return (const float*)(const GAS float*)raw(i); }
;     __device__ __forceinline__ unsigned char* ws() const { return (unsigned char*)(GAS unsigned char*)raw(N_INPUTS + 1); }
; __device__ __forceinline__ CvItem cv_decode(const PT& a, int l, int r) {
;     unsigned char* ws = a.ws(); CvItem it;
;     if (r < IT_WIN) { const int kb = r / 458, nb = r % 458, n0 = nb * 32;
;         int drow; if (n0 < 2048) drow = n0; else if (n0 < 5120) drow = NIN_MAIN + (n0 - 2048); else if (n0 < 8512) drow = 2048 + (n0 - 5120); else drow = 5632 + (n0 - 8512);
;         it = CvItem{a.in(I_W_IN) + (size_t)l * D * NIN, NIN, kb * 64, n0, (bf16_t*)(ws + WS_WIN + l * WIN_L), D, drow, a.in(I_NORM_MIX_G) + l * D}; return it; }
;     r -= IT_WIN;
;     if (r < 3 * IT_BR) { const int br = r / IT_BR; r -= br * IT_BR; const int kb = r / 64, nb = r % 64;
;         it = CvItem{a.in(br == 0 ? I_W_BR_A : (br == 1 ? I_W_BR_B : I_W_BR_C)) + (size_t)l * 1024 * D, D, kb * 64, nb * 32, (bf16_t*)(ws + WS_WBR + l * WBR_L) + (size_t)br * D * 1024, 1024, nb * 32, nullptr}; return it; }
;     r -= 3 * IT_BR;
;     if (r < IT_OUT) { const int kb = r / 64, nb = r % 64;
;         it = CvItem{a.in(I_W_OUT) + (size_t)l * D * D, D, kb * 64, nb * 32, (bf16_t*)(ws + WS_WOUT + l * WOUT_L), D, nb * 32, nullptr}; return it; }
;     r -= IT_OUT;
;     if (r < 2 * IT_GU) { const int up = r / IT_GU; r -= up * IT_GU; const int kb = r / 176, nb = r % 176, n0 = nb * 32;
;         it = CvItem{a.in(up ? I_W_FFN_UP : I_W_FFN_GATE) + (size_t)l * D * DFF, DFF, kb * 64, n0, (bf16_t*)(ws + WS_WGU + l * WGU_L), D, 256 * (n0 / 128) + (n0 % 128) + 128 * up, a.in(I_NORM_FFN_G) + l * D}; return it; }
;     r -= 2 * IT_GU;
;     { const int kb = r / 64, nb = r % 64;
;       it = CvItem{a.in(I_W_FFN_DOWN) + (size_t)l * DFF * D, D, kb * 64, nb * 32, (bf16_t*)(ws + WS_WDN + l * WDN_L), DFF, nb * 32, nullptr}; }
;     for (int it = 0; it < budget; ++it) {
;         unsigned r = 0; if (lane == 0) r = __hip_atomic_fetch_add(ctr, 2u, __ATOMIC_RELAXED, __HIP_MEMORY_SCOPE_AGENT);
;         r = (unsigned)__builtin_amdgcn_readfirstlane((int)r) + (unsigned)CV_PRO_ITEMS;
;         if (r >= (unsigned)IT_LAYER) break;
;         cv_pair(a, lds, l, (int)r, wave, lane);
.LcvqA_1381:
	s_mov_b32 s24, s100
	s_add_u32 s100, s100, 0xc00
	s_add_i32 s24, s24, 0xffffb400
	s_cmp_lt_u32 s24, 0xffff70c0
	s_mov_b64 s[2:3], -1
	s_cbranch_scc1 .LcvqA_1380
	v_mov_b32_e32 v2, 0x23a60
	s_add_i32 s15, s24, 0x8f40
	v_add_u32_e32 v2, 0, v2
	ds_read_b64 v[2:3], v2
	s_cmpk_gt_u32 s15, 0x393f
	s_waitcnt lgkmcnt(0)
	v_readfirstlane_b32 s20, v3
	v_readfirstlane_b32 s21, v2
	s_cbranch_scc0 .LcvqA_1399
	s_cmpk_gt_u32 s15, 0x453f
	s_cbranch_scc0 .LcvqA_1396
	s_cmpk_gt_u32 s15, 0x4d3f
	s_mov_b64 s[18:19], -1
	s_cbranch_scc0 .LcvqA_1393
	s_cmpk_gt_u32 s15, 0x793f
	s_cbranch_scc0 .LcvqA_1391
	v_mov_b32_e32 v2, 0x23a48
	s_and_b32 s2, s15, 0x7fffffc0
	v_add_u32_e32 v2, 0, v2
	ds_read_b64 v[2:3], v2
	s_add_i32 s14, s2, 0xffff86c0
	s_waitcnt lgkmcnt(0)
	v_readfirstlane_b32 s3, v2
	v_readfirstlane_b32 s2, v3
	s_add_u32 s30, s3, s34
	s_addc_u32 s31, s2, s33
	s_lshl_b32 s2, s15, 5
	s_and_b32 s25, s2, 0x7e0
	s_add_u32 s2, s21, s50
	s_addc_u32 s3, s20, s35
	s_add_u32 s12, s2, 0x1ea00000
	s_addc_u32 s13, s3, 0
	s_mov_b64 s[2:3], 0

; __device__ __forceinline__ int opaque_tid() { int t = threadIdx.x; asm volatile("" : "+v"(t)); return t; }
;     for (int it = 0; it < budget; ++it) {
;         unsigned r = 0; if (lane == 0) r = __hip_atomic_fetch_add(ctr, 2u, __ATOMIC_RELAXED, __HIP_MEMORY_SCOPE_AGENT);
;         r = (unsigned)__builtin_amdgcn_readfirstlane((int)r) + (unsigned)CV_PRO_ITEMS;
;         if (r >= (unsigned)IT_LAYER) break;
;         cv_pair(a, lds, l, (int)r, wave, lane);
;     }
; }
; __global__ void __launch_bounds__(NTHREADS, 2) mk_fwd(Args args) {
;     ...
;             if (l + 1 < DEPTH && !(G >= 256 && bid < 128)) { __syncthreads(); const int tid_ = opaque_tid(); convert_layer_queue(pt, lds, l + 1, cvq, tid_ >> 6, tid_ & 63); }
.LBB0_1377:
	s_cmp_eq_u32 s64, 0x63
	v_readlane_b32 s2, v253, 61
	s_cselect_b64 s[0:1], -1, 0
	v_readlane_b32 s3, v253, 62
	s_or_b64 s[0:1], s[2:3], s[0:1]
	v_readlane_b32 s2, v252, 4
	s_cmp_lg_u32 s2, 0x100
	s_cselect_b64 s[2:3], -1, 0
	s_or_b64 s[0:1], s[0:1], s[2:3]
	v_readlane_b32 s28, v254, 55
	s_mov_b32 s36, s64
	s_and_b64 vcc, exec, s[0:1]
	v_readlane_b32 s29, v254, 56
	s_cbranch_vccnz .LBB0_1470
	v_readlane_b32 s0, v254, 53
	v_readlane_b32 s1, v254, 54
	s_mov_b32 s3, s1
	s_lshl_b32 s2, s36, 6
	s_lshl_b64 s[0:1], s[2:3], 2
	v_readlane_b32 s4, v254, 60
	v_readlane_b32 s5, v254, 61
	s_add_u32 s0, s4, s0
	s_addc_u32 s1, s5, s1
	s_add_u32 s0, s0, 0x8000
	s_addc_u32 s1, s1, 0
	s_add_i32 s2, s36, 0
	s_mul_hi_u32 s33, s2, 0x2c00000
	s_mul_i32 s34, s2, 0x2c00000
	s_mul_hi_u32 s35, s2, 0x1600000
	s_mul_i32 s50, s2, 0x1600000
	s_lshl_b32 s6, s2, 11
	s_mov_b32 s7, s3
	s_lshl_b64 s[8:9], s[2:3], 24
	s_lshl_b64 s[10:11], s[2:3], 23
	s_mul_hi_u32 s51, s2, 0xc00000
	s_mul_i32 s52, s2, 0xc00000
	s_mul_hi_u32 s53, s2, 0x7280000
	s_mul_i32 s54, s2, 0x7280000
	s_mul_hi_u32 s55, s2, 0x3a00000
	v_writelane_b32 v254, s2, 53
	v_mov_b32_e32 v2, v0
	s_mul_i32 s56, s2, 0x3a00000
	v_writelane_b32 v254, s3, 54
	s_waitcnt vmcnt(0) lgkmcnt(0)
	s_barrier
	s_movk_i32 s2, 0x4200
	v_lshrrev_b32_e32 v1, 6, v2
	v_and_b32_e32 v3, 63, v2
	v_readfirstlane_b32 s100, v1
	v_readlane_b32 s101, v252, 0
	s_sub_u32 s101, s101, 128
	s_lshl_b32 s101, s101, 3
	s_add_u32 s100, s100, s101
	s_lshl_b32 s100, s100, 1
	s_add_u32 s100, s100, 0x3400
	v_mul_lo_u32 v1, v1, s2
	v_cmp_eq_u32_e64 s[40:41], 0, v3
	v_add_u32_e32 v3, 0, v1
	v_lshlrev_b32_e32 v1, 2, v2
	v_and_b32_e32 v66, 28, v1
	v_bfe_u32 v1, v2, 3, 3
	v_lshlrev_b32_e32 v2, 3, v2
	v_and_b32_e32 v68, 56, v2
	v_lshl_add_u32 v4, v66, 2, v3
	v_mul_u32_u24_e32 v5, 0x84, v1
	v_mul_u32_u24_e32 v2, 0x84, v68
	v_lshlrev_b32_e32 v6, 2, v1
	v_or_b32_e32 v67, 8, v1
	v_or_b32_e32 v69, 16, v1
	v_or_b32_e32 v71, 24, v1
	v_or_b32_e32 v73, 32, v1
	v_or_b32_e32 v75, 40, v1
	v_or_b32_e32 v77, 48, v1
	v_or_b32_e32 v79, 56, v1
	v_add3_u32 v81, v3, v2, v6
	s_mov_b32 s57, 0x3
	v_add_u32_e32 v83, v4, v5
	s_branch .LBB0_1381

;     __device__ __forceinline__ const float* in(int i) const { return (const float*)(const GAS float*)raw(i); }
;     __device__ __forceinline__ unsigned char* ws() const { return (unsigned char*)(GAS unsigned char*)raw(N_INPUTS + 1); }
; __device__ __forceinline__ CvItem cv_decode(const PT& a, int l, int r) {
;     unsigned char* ws = a.ws(); CvItem it;
;     if (r < IT_WIN) { const int kb = r / 458, nb = r % 458, n0 = nb * 32;
;         int drow; if (n0 < 2048) drow = n0; else if (n0 < 5120) drow = NIN_MAIN + (n0 - 2048); else if (n0 < 8512) drow = 2048 + (n0 - 5120); else drow = 5632 + (n0 - 8512);
;         it = CvItem{a.in(I_W_IN) + (size_t)l * D * NIN, NIN, kb * 64, n0, (bf16_t*)(ws + WS_WIN + l * WIN_L), D, drow, a.in(I_NORM_MIX_G) + l * D}; return it; }
;     r -= IT_WIN;
;     if (r < 3 * IT_BR) { const int br = r / IT_BR; r -= br * IT_BR; const int kb = r / 64, nb = r % 64;
;         it = CvItem{a.in(br == 0 ? I_W_BR_A : (br == 1 ? I_W_BR_B : I_W_BR_C)) + (size_t)l * 1024 * D, D, kb * 64, nb * 32, (bf16_t*)(ws + WS_WBR + l * WBR_L) + (size_t)br * D * 1024, 1024, nb * 32, nullptr}; return it; }
;     r -= 3 * IT_BR;
;     if (r < IT_OUT) { const int kb = r / 64, nb = r % 64;
;         it = CvItem{a.in(I_W_OUT) + (size_t)l * D * D, D, kb * 64, nb * 32, (bf16_t*)(ws + WS_WOUT + l * WOUT_L), D, nb * 32, nullptr}; return it; }
;     r -= IT_OUT;
;     if (r < 2 * IT_GU) { const int up = r / IT_GU; r -= up * IT_GU; const int kb = r / 176, nb = r % 176, n0 = nb * 32;
;         it = CvItem{a.in(up ? I_W_FFN_UP : I_W_FFN_GATE) + (size_t)l * D * DFF, DFF, kb * 64, n0, (bf16_t*)(ws + WS_WGU + l * WGU_L), D, 256 * (n0 / 128) + (n0 % 128) + 128 * up, a.in(I_NORM_FFN_G) + l * D}; return it; }
;     r -= 2 * IT_GU;
;     { const int kb = r / 64, nb = r % 64;
;       it = CvItem{a.in(I_W_FFN_DOWN) + (size_t)l * DFF * D, D, kb * 64, nb * 32, (bf16_t*)(ws + WS_WDN + l * WDN_L), DFF, nb * 32, nullptr}; }
;     for (int it = 0; it < budget; ++it) {
;         unsigned r = 0; if (lane == 0) r = __hip_atomic_fetch_add(ctr, 2u, __ATOMIC_RELAXED, __HIP_MEMORY_SCOPE_AGENT);
;         r = (unsigned)__builtin_amdgcn_readfirstlane((int)r) + (unsigned)CV_PRO_ITEMS;
;         if (r >= (unsigned)IT_LAYER) break;
;         cv_pair(a, lds, l, (int)r, wave, lane);
.LBB0_1381:
	s_mov_b32 s24, s100
	s_add_u32 s100, s100, 0x800
	s_add_i32 s24, s24, 0xffffb400
	s_cmp_lt_u32 s24, 0xffff70c0
	s_mov_b64 s[2:3], -1
	s_cbranch_scc1 .LBB0_1380
	v_mov_b32_e32 v2, 0x23a60
	s_add_i32 s15, s24, 0x8f40
	v_add_u32_e32 v2, 0, v2
	ds_read_b64 v[2:3], v2
	s_cmpk_gt_u32 s15, 0x393f
	s_waitcnt lgkmcnt(0)
	v_readfirstlane_b32 s20, v3
	v_readfirstlane_b32 s21, v2
	s_cbranch_scc0 .LBB0_1399
	s_cmpk_gt_u32 s15, 0x453f
	s_cbranch_scc0 .LBB0_1396
	s_cmpk_gt_u32 s15, 0x4d3f
	s_mov_b64 s[18:19], -1
	s_cbranch_scc0 .LBB0_1393
	s_cmpk_gt_u32 s15, 0x793f
	s_cbranch_scc0 .LBB0_1391
	v_mov_b32_e32 v2, 0x23a48
	s_and_b32 s2, s15, 0x7fffffc0
	v_add_u32_e32 v2, 0, v2
	ds_read_b64 v[2:3], v2
	s_add_i32 s14, s2, 0xffff86c0
	s_waitcnt lgkmcnt(0)
	v_readfirstlane_b32 s3, v2
	v_readfirstlane_b32 s2, v3
	s_add_u32 s30, s3, s34
	s_addc_u32 s31, s2, s33
	s_lshl_b32 s2, s15, 5
	s_and_b32 s25, s2, 0x7e0
	s_add_u32 s2, s21, s50
	s_addc_u32 s3, s20, s35
	s_add_u32 s12, s2, 0x1ea00000
	s_addc_u32 s13, s3, 0
	s_mov_b64 s[2:3], 0
